# v63 plus gate|up GEMM: same peeled first K iteration (counted waits skip the 8 SwiGLU epilogue stores)
# baseline (speedup 1.0000x reference)
; #define PG8_STAGE(bufoff, gbase, voff) do { _Pragma("unroll") for (int _i = 0; _i < 2; ++_i) \
;         __builtin_amdgcn_global_load_lds((const unsigned*)((const char*)(gbase) + (voff)[_i]), (PG8_LAS unsigned*)(lds + (bufoff) + ldsw + _i * 8192), 16, 0, 0); } while (0)
; #define PG8_WAIT_V(n) asm volatile("s_waitcnt vmcnt(" #n ")" ::: "memory")
; #define PG8_BAR __builtin_amdgcn_s_barrier()
; template <class Epi, class Sched, bool ALIGN_EPI = false, bool SP2 = false>
; __device__ __forceinline__ void gemm_phase(PG8_LAS unsigned char* lds, const Gemm g, const Sched& S, const Epi& E) {
;     ...
;     const int tid = tid_, wid = __builtin_amdgcn_readfirstlane(tid >> 6), lane = tid & 63, wr = wid >> 2, wc = wid & 3, fr = lane & 15, fq = lane >> 4;
;     const int K = g.K, nt = K / BK;
;     unsigned voffA[2], voffB[2];
; #pragma unroll
;     for (int i = 0; i < 2; ++i) { int R, C; stage_rc(tid * 16 + i * 8192, R, C); const int Rb = Epi::PERM ? ((R & ~31) + perm32(R & 31)) : R;
;         voffA[i] = (unsigned)(R * K + C) * 2u; voffB[i] = (unsigned)(Rb * K + C) * 2u; }
;     const size_t kstep = (size_t)(BK * 2);
;     const size_t hstep = (size_t)HALF * K * 2;
;     const size_t tstep = 2 * hstep;
;     const unsigned ldsw = (unsigned)wid * 1024u;
;     const int aoff = lds_byte(wr * 64 + fr, fq * 8), boff = lds_byte(wc * 32 + fr, fq * 8);
;     ...
;         PG8_STAGE(PG8_SB(0, 0), cB, voffB); PG8_STAGE(PG8_SB(0, 1), cB + hstep, voffB); PG8_STAGE(PG8_SA(0, 0), cA, voffA); PG8_STAGE(PG8_SA(0, 1), cA + hstep, voffA);
;         if (wr == 1) PG8_BAR;
;         PG8_WAIT_V(2); PG8_BAR;
;         PG8_STAGE(PG8_SB(1, 0), cB + kstep, voffB); PG8_STAGE(PG8_SA(1, 0), cA + kstep, voffA); PG8_STAGE(PG8_SB(1, 1), cB + hstep + kstep, voffB);
;         PG8_WAIT_V(6); PG8_BAR;
.LBB0_295:
	s_mov_b32 s32, 0
	s_mov_b32 s32, 0
	v_and_b32_e32 v19, 15, v18
	v_lshrrev_b32_e32 v18, 1, v18
	v_and_b32_e32 v18, 24, v18
	v_lshlrev_b32_e32 v20, 1, v18
	s_add_u32 s6, s6, 0x3ae00000
	v_lshl_or_b32 v1, s1, 6, v19
	v_lshl_or_b32 v20, v19, 6, v20
	v_lshlrev_b32_e32 v19, 2, v19
	s_sext_i32_i16 s35, s0
	s_addc_u32 s7, s7, 0
	s_lshl_b32 s0, s1, 13
	v_and_b32_e32 v21, 32, v19
	s_waitcnt vmcnt(0)
	v_bitop3_b32 v22, v20, s0, v21 bitop3:0xde
	s_lshl_b32 s0, s9, 5
	s_and_b32 s0, s0, 0x60
	s_add_i32 m0, s47, 0x18000
	v_lshl_add_u64 v[10:11], v[10:11], 0, s[16:17]
	s_lshl_b32 s9, s0, 7
	s_waitcnt vmcnt(2)
	s_barrier
	global_load_lds_dwordx4 v[10:11], off
	v_lshl_add_u64 v[8:9], v[8:9], 0, s[16:17]
	s_add_i32 m0, s47, 0x1a000
	s_add_i32 s51, s47, 0x8000
	s_add_i32 s53, s47, 0xa000
	global_load_lds_dwordx4 v[8:9], off
	v_lshl_add_u64 v[4:5], v[4:5], 0, s[16:17]
	s_mov_b32 m0, s51
	s_add_u32 s10, s38, 0x80080
	global_load_lds_dwordx4 v[4:5], off
	v_lshl_add_u64 v[4:5], v[6:7], 0, s[16:17]
	s_mov_b32 m0, s53
	s_addc_u32 s11, s39, 0
	global_load_lds_dwordx4 v[4:5], off
	s_add_i32 m0, s47, 0x1c000
	v_lshl_add_u64 v[4:5], s[10:11], 0, v[2:3]
	global_load_lds_dwordx4 v[4:5], off
	v_lshl_add_u64 v[4:5], s[10:11], 0, v[132:133]
	s_add_i32 m0, s47, 0x1e000
	s_cmpk_lt_u32 s8, 0x100
	global_load_lds_dwordx4 v[4:5], off
	v_lshlrev_b32_e32 v4, 15, v16
	v_and_b32_e32 v4, 0xffff0000, v4
	v_lshl_add_u32 v4, v15, 12, v4
	v_and_b32_e32 v5, 1, v16
	v_lshl_or_b32 v4, v5, 6, v4
	v_lshl_add_u32 v138, v17, 1, v4
	v_lshlrev_b32_e32 v4, 15, v12
	v_bitop3_b32 v150, v20, s9, v21 bitop3:0xde
	s_cselect_b64 s[8:9], -1, 0
	s_lshl_b32 s1, s1, 8
	v_and_b32_e32 v4, 0xffff0000, v4
	s_waitcnt vmcnt(6)
	s_add_i32 s1, s1, 0
	v_lshl_add_u32 v4, v13, 12, v4
	v_and_b32_e32 v5, 1, v12
	s_add_i32 s1, s1, 0x20400
	v_lshl_or_b32 v4, v5, 6, v4
	s_ashr_i32 s54, s26, 31
	v_add_u32_e32 v151, s1, v19
	v_or_b32_e32 v152, s0, v18
	v_mov_b32_e32 v139, v3
	v_lshl_add_u32 v140, v14, 1, v4
	v_mov_b32_e32 v141, v3
	s_mov_b32 s55, 0
	v_add_u32_e32 v153, 0, v22
	s_barrier
	s_branch .LBB0_298

;     __device__ __forceinline__ bool next(int i, Unit& u) const { if (!StaticOrder::next(i / 3, u)) return false; u.aux = i % 3; return true; }
; #define PG8_STAGE(bufoff, gbase, voff) do { _Pragma("unroll") for (int _i = 0; _i < 2; ++_i) \
;         __builtin_amdgcn_global_load_lds((const unsigned*)((const char*)(gbase) + (voff)[_i]), (PG8_LAS unsigned*)(lds + (bufoff) + ldsw + _i * 8192), 16, 0, 0); } while (0)
; #define PG8_LDA(dst, b, h) do { _Pragma("unroll") for (int m = 0; m < 4; ++m) _Pragma("unroll") for (int k = 0; k < 2; ++k) dst[m][k] = *(const PG8_LAS bf16x8*)(lds + PG8_SA(b, h) + aoff + m * 2048 + k * 1024); } while (0)
; #define PG8_LDB(dst, b, h) do { _Pragma("unroll") for (int n = 0; n < 2; ++n) _Pragma("unroll") for (int k = 0; k < 2; ++k) dst[n][k] = *(const PG8_LAS bf16x8*)(lds + PG8_SB(b, h) + boff + n * 2048 + k * 1024); } while (0)
; #define PG8_WAIT_V(n) asm volatile("s_waitcnt vmcnt(" #n ")" ::: "memory")
; template <class Epi, class Sched, bool ALIGN_EPI = false, bool SP2 = false>
; __device__ __forceinline__ void gemm_phase(PG8_LAS unsigned char* lds, const Gemm g, const Sched& S, const Epi& E) {
;     ...
;         const bool has_next = S.next(ui + 1, nxt);
;         const char* nA = cA; const char* nB = cB; if (has_next) S.bases(g, nxt, tstep, nA, nB);
;         for (int t = 0; t < nt; t += 2) {
;             const bool last = (t == nt - 2);
;             const char* a1 = cA + (size_t)(t + 1) * kstep;
;             const char* a2 = last ? nA : cA + (size_t)(t + 2) * kstep; const char* b2 = last ? nB : cB + (size_t)(t + 2) * kstep;
;             const char* a3 = a2 + kstep; const char* b3 = b2 + kstep;
;             if (last && has_next) S.a_ready(nxt);
;             if constexpr (SP2) {
;             PG8_LDB(B0, 0, 0); PG8_LDB(B1, 0, 1); PG8_SCHED; PG8_LDA(At, 0, 0); PG8_STAGE(PG8_SA(1, 1), a1 + hstep, voffA);
;             PG8_WAIT_V(8); PG8_WAIT_L(0); PG8_BAR; PG8_MMA(0, 0, At, B0); PG8_MMA(0, 1, At, B1); PG8_BAR; PG8_SCHED;
;     ...
;         bool zero_acc = true; if constexpr (Epi::KEEP_ACC) zero_acc = (cur.aux == 2);
;         if (zero_acc) {
; #pragma unroll
;         for (int a = 0; a < 2; ++a)
; #pragma unroll
;             for (int b = 0; b < 2; ++b)
; #pragma unroll
;                 for (int m = 0; m < 4; ++m)
; #pragma unroll
;                     for (int n = 0; n < 2; ++n) acc[a][b][m][n] = (f32x4){0.f, 0.f, 0.f, 0.f};
.LBB0_300:
	s_ashr_i32 s13, s12, 31
	s_lshl_b64 s[28:29], s[12:13], 20
	s_add_u32 s28, s43, s28
	s_addc_u32 s29, s44, s29
	s_ashr_i32 s11, s10, 31
	s_lshl_b64 s[30:31], s[10:11], 20
	s_add_u32 s30, s45, s30
	s_addc_u32 s31, s46, s31
	s_and_b64 s[40:41], s[0:1], exec
	s_cselect_b32 s11, s29, s37
	s_cselect_b32 s13, s28, s36
	s_cselect_b32 s56, s31, s39
	s_cselect_b32 s57, s30, s38
	s_add_u32 s36, s36, 0x80080
	s_addc_u32 s37, s37, 0
	s_add_u32 s58, s38, 0x100
	v_mov_b32_e32 v4, 0
	s_addc_u32 s59, s39, 0
	s_mov_b32 s60, -2
	v_mov_b32_e32 v5, v4
	v_mov_b32_e32 v6, v4
	v_mov_b32_e32 v7, v4
	v_mov_b32_e32 v12, v4
	v_mov_b32_e32 v13, v4
	v_mov_b32_e32 v14, v4
	v_mov_b32_e32 v15, v4
	v_mov_b32_e32 v20, v4
	v_mov_b32_e32 v21, v4
	v_mov_b32_e32 v22, v4
	v_mov_b32_e32 v23, v4
	v_mov_b32_e32 v28, v4
	v_mov_b32_e32 v29, v4
	v_mov_b32_e32 v30, v4
	v_mov_b32_e32 v31, v4
	v_mov_b32_e32 v36, v4
	v_mov_b32_e32 v37, v4
	v_mov_b32_e32 v38, v4
	v_mov_b32_e32 v39, v4
	v_mov_b32_e32 v44, v4
	v_mov_b32_e32 v45, v4
	v_mov_b32_e32 v46, v4
	v_mov_b32_e32 v47, v4
	v_mov_b32_e32 v52, v4
	v_mov_b32_e32 v53, v4
	v_mov_b32_e32 v54, v4
	v_mov_b32_e32 v55, v4
	v_mov_b32_e32 v60, v4
	v_mov_b32_e32 v61, v4
	v_mov_b32_e32 v62, v4
	v_mov_b32_e32 v63, v4
	v_mov_b32_e32 v8, v4
	v_mov_b32_e32 v9, v4
	v_mov_b32_e32 v10, v4
	v_mov_b32_e32 v11, v4
	v_mov_b32_e32 v16, v4
	v_mov_b32_e32 v17, v4
	v_mov_b32_e32 v18, v4
	v_mov_b32_e32 v19, v4
	v_mov_b32_e32 v24, v4
	v_mov_b32_e32 v25, v4
	v_mov_b32_e32 v26, v4
	v_mov_b32_e32 v27, v4
	v_mov_b32_e32 v32, v4
	v_mov_b32_e32 v33, v4
	v_mov_b32_e32 v34, v4
	v_mov_b32_e32 v35, v4
	v_mov_b32_e32 v40, v4
	v_mov_b32_e32 v41, v4
	v_mov_b32_e32 v42, v4
	v_mov_b32_e32 v43, v4
	v_mov_b32_e32 v48, v4
	v_mov_b32_e32 v49, v4
	v_mov_b32_e32 v50, v4
	v_mov_b32_e32 v51, v4
	v_mov_b32_e32 v56, v4
	v_mov_b32_e32 v57, v4
	v_mov_b32_e32 v58, v4
	v_mov_b32_e32 v59, v4
	v_mov_b32_e32 v64, v4
	v_mov_b32_e32 v65, v4
	v_mov_b32_e32 v66, v4
	v_mov_b32_e32 v67, v4
	v_mov_b32_e32 v68, v4
	v_mov_b32_e32 v69, v4
	v_mov_b32_e32 v70, v4
	v_mov_b32_e32 v71, v4
	v_mov_b32_e32 v76, v4
	v_mov_b32_e32 v77, v4
	v_mov_b32_e32 v78, v4
	v_mov_b32_e32 v79, v4
	v_mov_b32_e32 v84, v4
	v_mov_b32_e32 v85, v4
	v_mov_b32_e32 v86, v4
	v_mov_b32_e32 v87, v4
	v_mov_b32_e32 v92, v4
	v_mov_b32_e32 v93, v4
	v_mov_b32_e32 v94, v4
	v_mov_b32_e32 v95, v4
	v_mov_b32_e32 v100, v4
	v_mov_b32_e32 v101, v4
	v_mov_b32_e32 v102, v4
	v_mov_b32_e32 v103, v4
	v_mov_b32_e32 v108, v4
	v_mov_b32_e32 v109, v4
	v_mov_b32_e32 v110, v4
	v_mov_b32_e32 v111, v4
	v_mov_b32_e32 v116, v4
	v_mov_b32_e32 v117, v4
	v_mov_b32_e32 v118, v4
	v_mov_b32_e32 v119, v4
	v_mov_b32_e32 v124, v4
	v_mov_b32_e32 v125, v4
	v_mov_b32_e32 v126, v4
	v_mov_b32_e32 v127, v4
	v_mov_b32_e32 v72, v4
	v_mov_b32_e32 v73, v4
	v_mov_b32_e32 v74, v4
	v_mov_b32_e32 v75, v4
	v_mov_b32_e32 v80, v4
	v_mov_b32_e32 v81, v4
	v_mov_b32_e32 v82, v4
	v_mov_b32_e32 v83, v4
	v_mov_b32_e32 v88, v4
	v_mov_b32_e32 v89, v4
	v_mov_b32_e32 v90, v4
	v_mov_b32_e32 v91, v4
	v_mov_b32_e32 v96, v4
	v_mov_b32_e32 v97, v4
	v_mov_b32_e32 v98, v4
	v_mov_b32_e32 v99, v4
	v_mov_b32_e32 v104, v4
	v_mov_b32_e32 v105, v4
	v_mov_b32_e32 v106, v4
	v_mov_b32_e32 v107, v4
	v_mov_b32_e32 v112, v4
	v_mov_b32_e32 v113, v4
	v_mov_b32_e32 v114, v4
	v_mov_b32_e32 v115, v4
	v_mov_b32_e32 v120, v4
	v_mov_b32_e32 v121, v4
	v_mov_b32_e32 v122, v4
	v_mov_b32_e32 v123, v4
	v_mov_b32_e32 v128, v4
	v_mov_b32_e32 v129, v4
	v_mov_b32_e32 v130, v4
	v_mov_b32_e32 v131, v4
	v_add_u32_e32 v249, 0x10000, v150
	ds_read_b128 v[142:145], v249
	ds_read_b128 v[146:149], v249 offset:1024
	ds_read_b128 v[154:157], v249 offset:2048
	ds_read_b128 v[158:161], v249 offset:3072
	s_cmp_eq_u32 s32, 0
	s_cbranch_scc1 .LBB0_301
	s_add_u32 s38, s36, 0xfff80080
	s_addc_u32 s39, s37, -1
	s_add_i32 s61, 0, 0x10000
	s_cmp_eq_u32 s60, 28
	s_cselect_b32 s41, s11, s39
	s_cselect_b32 s40, s13, s38
	s_cselect_b32 s39, s56, s59
	s_cselect_b32 s38, s57, s58
	s_add_i32 s64, 0, 0x14000
	ds_read_b128 v[174:177], v249 offset:16384
	ds_read_b128 v[178:181], v249 offset:17408
	ds_read_b128 v[204:207], v249 offset:18432
	ds_read_b128 v[208:211], v249 offset:19456
	s_add_i32 m0, s47, 0xc000
	ds_read_b128 v[212:215], v153
	ds_read_b128 v[216:219], v153 offset:1024
	ds_read_b128 v[220:223], v153 offset:2048
	ds_read_b128 v[224:227], v153 offset:3072
	ds_read_b128 v[228:231], v153 offset:4096
	ds_read_b128 v[232:235], v153 offset:5120
	ds_read_b128 v[236:239], v153 offset:6144
	ds_read_b128 v[240:243], v153 offset:7168
	global_load_lds_dwordx4 v138, s[36:37]
	s_add_i32 m0, s47, 0xe000
	s_nop 0
	global_load_lds_dwordx4 v140, s[36:37]
	s_waitcnt vmcnt(16) lgkmcnt(0)
	s_setprio 0
	s_barrier
; #define PG8_STAGE(bufoff, gbase, voff) do { _Pragma("unroll") for (int _i = 0; _i < 2; ++_i) \
;         __builtin_amdgcn_global_load_lds((const unsigned*)((const char*)(gbase) + (voff)[_i]), (PG8_LAS unsigned*)(lds + (bufoff) + ldsw + _i * 8192), 16, 0, 0); } while (0)
; #define PG8_LDA(dst, b, h) do { _Pragma("unroll") for (int m = 0; m < 4; ++m) _Pragma("unroll") for (int k = 0; k < 2; ++k) dst[m][k] = *(const PG8_LAS bf16x8*)(lds + PG8_SA(b, h) + aoff + m * 2048 + k * 1024); } while (0)
; #define PG8_LDB(dst, b, h) do { _Pragma("unroll") for (int n = 0; n < 2; ++n) _Pragma("unroll") for (int k = 0; k < 2; ++k) dst[n][k] = *(const PG8_LAS bf16x8*)(lds + PG8_SB(b, h) + boff + n * 2048 + k * 1024); } while (0)
; #define PG8_MMA(ai, bj, At, Bt) do { __builtin_amdgcn_s_setprio(1); _Pragma("unroll") for (int m = 0; m < 4; ++m) _Pragma("unroll") for (int n = 0; n < 2; ++n) _Pragma("unroll") for (int k = 0; k < 2; ++k) \
;         acc[ai][bj][m][n] = __builtin_amdgcn_mfma_f32_16x16x32_bf16(Bt[n][k], At[m][k], acc[ai][bj][m][n], 0, 0, 0); __builtin_amdgcn_s_setprio(0); } while (0)
; #define PG8_WAIT_V(n) asm volatile("s_waitcnt vmcnt(" #n ")" ::: "memory")
; #define PG8_WAIT_L(n) asm volatile("s_waitcnt lgkmcnt(" #n ")" ::: "memory")
; #define PG8_BAR __builtin_amdgcn_s_barrier()
; #define PG8_SCHED __builtin_amdgcn_sched_barrier(0)
; template <class Epi, class Sched, bool ALIGN_EPI = false, bool SP2 = false>
; __device__ __forceinline__ void gemm_phase(PG8_LAS unsigned char* lds, const Gemm g, const Sched& S, const Epi& E) {
;     ...
;             PG8_WAIT_V(8); PG8_WAIT_L(0); PG8_BAR; PG8_MMA(0, 0, At, B0); PG8_MMA(0, 1, At, B1); PG8_BAR; PG8_SCHED;
;             PG8_LDA(At, 0, 1); PG8_STAGE(PG8_SB(0, 0), b2, voffB); PG8_STAGE(PG8_SB(0, 1), b2 + hstep, voffB); PG8_STAGE(PG8_SA(0, 0), a2, voffA);
;             PG8_WAIT_V(8); PG8_WAIT_L(0); PG8_BAR; PG8_MMA(1, 0, At, B0); PG8_MMA(1, 1, At, B1); PG8_BAR; PG8_SCHED;
;             PG8_LDB(B0, 1, 0); PG8_LDB(B1, 1, 1); PG8_SCHED; PG8_LDA(At, 1, 0); PG8_STAGE(PG8_SA(0, 1), a2 + hstep, voffA);
	v_mfma_f32_16x16x32_bf16 v[128:131], v[142:145], v[212:215], v[128:131]
	v_mfma_f32_16x16x32_bf16 v[120:123], v[154:157], v[212:215], v[120:123]
	v_mfma_f32_16x16x32_bf16 v[112:115], v[142:145], v[220:223], v[112:115]
	v_mfma_f32_16x16x32_bf16 v[104:107], v[154:157], v[220:223], v[104:107]
	v_mfma_f32_16x16x32_bf16 v[96:99], v[142:145], v[228:231], v[96:99]
	v_mfma_f32_16x16x32_bf16 v[88:91], v[154:157], v[228:231], v[88:91]
	v_mfma_f32_16x16x32_bf16 v[80:83], v[142:145], v[236:239], v[80:83]
	v_mfma_f32_16x16x32_bf16 v[72:75], v[154:157], v[236:239], v[72:75]
	v_mfma_f32_16x16x32_bf16 v[128:131], v[146:149], v[216:219], v[128:131]
	v_mfma_f32_16x16x32_bf16 v[120:123], v[158:161], v[216:219], v[120:123]
	v_mfma_f32_16x16x32_bf16 v[112:115], v[146:149], v[224:227], v[112:115]
	v_mfma_f32_16x16x32_bf16 v[104:107], v[158:161], v[224:227], v[104:107]
	v_mfma_f32_16x16x32_bf16 v[96:99], v[146:149], v[232:235], v[96:99]
	v_mfma_f32_16x16x32_bf16 v[88:91], v[158:161], v[232:235], v[88:91]
	v_mfma_f32_16x16x32_bf16 v[80:83], v[146:149], v[240:243], v[80:83]
	v_mfma_f32_16x16x32_bf16 v[72:75], v[158:161], v[240:243], v[72:75]
	v_mfma_f32_16x16x32_bf16 v[124:127], v[174:177], v[212:215], v[124:127]
	v_mfma_f32_16x16x32_bf16 v[116:119], v[204:207], v[212:215], v[116:119]
	v_mfma_f32_16x16x32_bf16 v[108:111], v[174:177], v[220:223], v[108:111]
	v_mfma_f32_16x16x32_bf16 v[100:103], v[204:207], v[220:223], v[100:103]
	v_mfma_f32_16x16x32_bf16 v[92:95], v[174:177], v[228:231], v[92:95]
	v_mfma_f32_16x16x32_bf16 v[84:87], v[204:207], v[228:231], v[84:87]
	v_mfma_f32_16x16x32_bf16 v[76:79], v[174:177], v[236:239], v[76:79]
	v_mfma_f32_16x16x32_bf16 v[68:71], v[204:207], v[236:239], v[68:71]
	v_mfma_f32_16x16x32_bf16 v[124:127], v[178:181], v[216:219], v[124:127]
	v_mfma_f32_16x16x32_bf16 v[116:119], v[208:211], v[216:219], v[116:119]
	v_mfma_f32_16x16x32_bf16 v[108:111], v[178:181], v[224:227], v[108:111]
	v_mfma_f32_16x16x32_bf16 v[100:103], v[208:211], v[224:227], v[100:103]
	v_mfma_f32_16x16x32_bf16 v[92:95], v[178:181], v[232:235], v[92:95]
	v_mfma_f32_16x16x32_bf16 v[84:87], v[208:211], v[232:235], v[84:87]
	v_mfma_f32_16x16x32_bf16 v[76:79], v[178:181], v[240:243], v[76:79]
	v_mfma_f32_16x16x32_bf16 v[68:71], v[208:211], v[240:243], v[68:71]
	s_setprio 3
	s_barrier
	s_add_i32 s61, s61, s42
	s_mov_b32 m0, s61
	ds_read_b128 v[212:215], v153 offset:16384
	ds_read_b128 v[216:219], v153 offset:17408
	ds_read_b128 v[220:223], v153 offset:18432
	ds_read_b128 v[224:227], v153 offset:19456
	ds_read_b128 v[228:231], v153 offset:20480
	ds_read_b128 v[232:235], v153 offset:21504
	ds_read_b128 v[236:239], v153 offset:22528
	ds_read_b128 v[240:243], v153 offset:23552
	global_load_lds_dwordx4 v2, s[38:39]
	s_add_i32 m0, s61, 0x2000
	s_add_u32 s62, s38, 0x80000
	s_addc_u32 s63, s39, 0
	s_add_i32 s61, s64, s42
	global_load_lds_dwordx4 v132, s[38:39]
	s_mov_b32 m0, s61
	s_nop 0
	global_load_lds_dwordx4 v2, s[62:63]
	s_add_i32 m0, s61, 0x2000
	s_nop 0
	global_load_lds_dwordx4 v132, s[62:63]
	s_mov_b32 m0, s47
	s_nop 0
	global_load_lds_dwordx4 v136, s[40:41]
	s_mov_b32 m0, s48
	s_nop 0
	global_load_lds_dwordx4 v134, s[40:41]
	s_waitcnt vmcnt(16) lgkmcnt(0)
	s_setprio 0
	s_barrier
	v_mfma_f32_16x16x32_bf16 v[64:67], v[142:145], v[212:215], v[64:67]
	v_mfma_f32_16x16x32_bf16 v[56:59], v[154:157], v[212:215], v[56:59]
	v_mfma_f32_16x16x32_bf16 v[48:51], v[142:145], v[220:223], v[48:51]
	v_mfma_f32_16x16x32_bf16 v[40:43], v[154:157], v[220:223], v[40:43]
	v_mfma_f32_16x16x32_bf16 v[32:35], v[142:145], v[228:231], v[32:35]
	v_mfma_f32_16x16x32_bf16 v[24:27], v[154:157], v[228:231], v[24:27]
	v_mfma_f32_16x16x32_bf16 v[16:19], v[142:145], v[236:239], v[16:19]
	v_mfma_f32_16x16x32_bf16 v[8:11], v[154:157], v[236:239], v[8:11]
	v_mfma_f32_16x16x32_bf16 v[64:67], v[146:149], v[216:219], v[64:67]
	v_mfma_f32_16x16x32_bf16 v[56:59], v[158:161], v[216:219], v[56:59]
	v_mfma_f32_16x16x32_bf16 v[48:51], v[146:149], v[224:227], v[48:51]
	v_mfma_f32_16x16x32_bf16 v[40:43], v[158:161], v[224:227], v[40:43]
	v_mfma_f32_16x16x32_bf16 v[32:35], v[146:149], v[232:235], v[32:35]
	v_mfma_f32_16x16x32_bf16 v[24:27], v[158:161], v[232:235], v[24:27]
	v_mfma_f32_16x16x32_bf16 v[16:19], v[146:149], v[240:243], v[16:19]
	v_mfma_f32_16x16x32_bf16 v[8:11], v[158:161], v[240:243], v[8:11]
	v_mfma_f32_16x16x32_bf16 v[60:63], v[174:177], v[212:215], v[60:63]
	ds_read_b128 v[142:145], v249 offset:32768
	v_mfma_f32_16x16x32_bf16 v[52:55], v[204:207], v[212:215], v[52:55]
	ds_read_b128 v[146:149], v249 offset:33792
	v_mfma_f32_16x16x32_bf16 v[44:47], v[174:177], v[220:223], v[44:47]
	ds_read_b128 v[154:157], v249 offset:34816
	v_mfma_f32_16x16x32_bf16 v[36:39], v[204:207], v[220:223], v[36:39]
	ds_read_b128 v[158:161], v249 offset:35840
	v_mfma_f32_16x16x32_bf16 v[28:31], v[174:177], v[228:231], v[28:31]
	v_mfma_f32_16x16x32_bf16 v[20:23], v[204:207], v[228:231], v[20:23]
	v_mfma_f32_16x16x32_bf16 v[12:15], v[174:177], v[236:239], v[12:15]
	v_mfma_f32_16x16x32_bf16 v[4:7], v[204:207], v[236:239], v[4:7]
	v_mfma_f32_16x16x32_bf16 v[60:63], v[178:181], v[216:219], v[60:63]
	v_mfma_f32_16x16x32_bf16 v[52:55], v[208:211], v[216:219], v[52:55]
	v_mfma_f32_16x16x32_bf16 v[44:47], v[178:181], v[224:227], v[44:47]
	v_mfma_f32_16x16x32_bf16 v[36:39], v[208:211], v[224:227], v[36:39]
	v_mfma_f32_16x16x32_bf16 v[28:31], v[178:181], v[232:235], v[28:31]
	v_mfma_f32_16x16x32_bf16 v[20:23], v[208:211], v[232:235], v[20:23]
	v_mfma_f32_16x16x32_bf16 v[12:15], v[178:181], v[240:243], v[12:15]
	v_mfma_f32_16x16x32_bf16 v[4:7], v[208:211], v[240:243], v[4:7]
	s_setprio 3
	s_barrier
; #define PG8_STAGE(bufoff, gbase, voff) do { _Pragma("unroll") for (int _i = 0; _i < 2; ++_i) \
;         __builtin_amdgcn_global_load_lds((const unsigned*)((const char*)(gbase) + (voff)[_i]), (PG8_LAS unsigned*)(lds + (bufoff) + ldsw + _i * 8192), 16, 0, 0); } while (0)
; #define PG8_LDA(dst, b, h) do { _Pragma("unroll") for (int m = 0; m < 4; ++m) _Pragma("unroll") for (int k = 0; k < 2; ++k) dst[m][k] = *(const PG8_LAS bf16x8*)(lds + PG8_SA(b, h) + aoff + m * 2048 + k * 1024); } while (0)
; #define PG8_LDB(dst, b, h) do { _Pragma("unroll") for (int n = 0; n < 2; ++n) _Pragma("unroll") for (int k = 0; k < 2; ++k) dst[n][k] = *(const PG8_LAS bf16x8*)(lds + PG8_SB(b, h) + boff + n * 2048 + k * 1024); } while (0)
; #define PG8_MMA(ai, bj, At, Bt) do { __builtin_amdgcn_s_setprio(1); _Pragma("unroll") for (int m = 0; m < 4; ++m) _Pragma("unroll") for (int n = 0; n < 2; ++n) _Pragma("unroll") for (int k = 0; k < 2; ++k) \
;         acc[ai][bj][m][n] = __builtin_amdgcn_mfma_f32_16x16x32_bf16(Bt[n][k], At[m][k], acc[ai][bj][m][n], 0, 0, 0); __builtin_amdgcn_s_setprio(0); } while (0)
; #define PG8_WAIT_V(n) asm volatile("s_waitcnt vmcnt(" #n ")" ::: "memory")
; #define PG8_WAIT_L(n) asm volatile("s_waitcnt lgkmcnt(" #n ")" ::: "memory")
; #define PG8_BAR __builtin_amdgcn_s_barrier()
; #define PG8_SCHED __builtin_amdgcn_sched_barrier(0)
; template <class Epi, class Sched, bool ALIGN_EPI = false, bool SP2 = false>
; __device__ __forceinline__ void gemm_phase(PG8_LAS unsigned char* lds, const Gemm g, const Sched& S, const Epi& E) {
;     ...
;             PG8_LDB(B0, 1, 0); PG8_LDB(B1, 1, 1); PG8_SCHED; PG8_LDA(At, 1, 0); PG8_STAGE(PG8_SA(0, 1), a2 + hstep, voffA);
;             PG8_WAIT_V(8); PG8_WAIT_L(0); PG8_BAR; PG8_MMA(0, 0, At, B0); PG8_MMA(0, 1, At, B1); PG8_BAR; PG8_SCHED;
;             PG8_LDA(At, 1, 1); PG8_STAGE(PG8_SB(1, 0), b3, voffB); PG8_STAGE(PG8_SB(1, 1), b3 + hstep, voffB); PG8_STAGE(PG8_SA(1, 0), a3, voffA);
;             PG8_WAIT_V(8); PG8_WAIT_L(0); PG8_BAR; PG8_MMA(1, 0, At, B0); PG8_MMA(1, 1, At, B1); PG8_BAR; PG8_SCHED;
	s_add_i32 s61, 0, 0x18000
	s_add_i32 s62, 0, 0x1c000
	ds_read_b128 v[174:177], v249 offset:49152
	ds_read_b128 v[178:181], v249 offset:50176
	ds_read_b128 v[204:207], v249 offset:51200
	ds_read_b128 v[208:211], v249 offset:52224
	s_add_u32 s100, s40, 0x80
	s_addc_u32 s101, s41, 0
	s_add_u32 s40, s40, 0x80000
	s_addc_u32 s41, s41, 0
	s_mov_b32 m0, s49
	ds_read_b128 v[212:215], v153 offset:32768
	ds_read_b128 v[216:219], v153 offset:33792
	ds_read_b128 v[220:223], v153 offset:34816
	ds_read_b128 v[224:227], v153 offset:35840
	ds_read_b128 v[228:231], v153 offset:36864
	ds_read_b128 v[232:235], v153 offset:37888
	ds_read_b128 v[236:239], v153 offset:38912
	ds_read_b128 v[240:243], v153 offset:39936
	global_load_lds_dwordx4 v136, s[40:41]
	s_mov_b32 m0, s50
	s_nop 0
	global_load_lds_dwordx4 v134, s[40:41]
	s_waitcnt vmcnt(8) lgkmcnt(0)
	s_setprio 0
	s_barrier
	v_mfma_f32_16x16x32_bf16 v[128:131], v[142:145], v[212:215], v[128:131]
	v_mfma_f32_16x16x32_bf16 v[120:123], v[154:157], v[212:215], v[120:123]
	v_mfma_f32_16x16x32_bf16 v[112:115], v[142:145], v[220:223], v[112:115]
	v_mfma_f32_16x16x32_bf16 v[104:107], v[154:157], v[220:223], v[104:107]
	v_mfma_f32_16x16x32_bf16 v[96:99], v[142:145], v[228:231], v[96:99]
	v_mfma_f32_16x16x32_bf16 v[88:91], v[154:157], v[228:231], v[88:91]
	v_mfma_f32_16x16x32_bf16 v[80:83], v[142:145], v[236:239], v[80:83]
	v_mfma_f32_16x16x32_bf16 v[72:75], v[154:157], v[236:239], v[72:75]
	v_mfma_f32_16x16x32_bf16 v[128:131], v[146:149], v[216:219], v[128:131]
	v_mfma_f32_16x16x32_bf16 v[120:123], v[158:161], v[216:219], v[120:123]
	v_mfma_f32_16x16x32_bf16 v[112:115], v[146:149], v[224:227], v[112:115]
	v_mfma_f32_16x16x32_bf16 v[104:107], v[158:161], v[224:227], v[104:107]
	v_mfma_f32_16x16x32_bf16 v[96:99], v[146:149], v[232:235], v[96:99]
	v_mfma_f32_16x16x32_bf16 v[88:91], v[158:161], v[232:235], v[88:91]
	v_mfma_f32_16x16x32_bf16 v[80:83], v[146:149], v[240:243], v[80:83]
	v_mfma_f32_16x16x32_bf16 v[72:75], v[158:161], v[240:243], v[72:75]
	v_mfma_f32_16x16x32_bf16 v[124:127], v[174:177], v[212:215], v[124:127]
	v_mfma_f32_16x16x32_bf16 v[116:119], v[204:207], v[212:215], v[116:119]
	v_mfma_f32_16x16x32_bf16 v[108:111], v[174:177], v[220:223], v[108:111]
	v_mfma_f32_16x16x32_bf16 v[100:103], v[204:207], v[220:223], v[100:103]
	v_mfma_f32_16x16x32_bf16 v[92:95], v[174:177], v[228:231], v[92:95]
	v_mfma_f32_16x16x32_bf16 v[84:87], v[204:207], v[228:231], v[84:87]
	v_mfma_f32_16x16x32_bf16 v[76:79], v[174:177], v[236:239], v[76:79]
	v_mfma_f32_16x16x32_bf16 v[68:71], v[204:207], v[236:239], v[68:71]
	v_mfma_f32_16x16x32_bf16 v[124:127], v[178:181], v[216:219], v[124:127]
	v_mfma_f32_16x16x32_bf16 v[116:119], v[208:211], v[216:219], v[116:119]
	v_mfma_f32_16x16x32_bf16 v[108:111], v[178:181], v[224:227], v[108:111]
	v_mfma_f32_16x16x32_bf16 v[100:103], v[208:211], v[224:227], v[100:103]
	v_mfma_f32_16x16x32_bf16 v[92:95], v[178:181], v[232:235], v[92:95]
	v_mfma_f32_16x16x32_bf16 v[84:87], v[208:211], v[232:235], v[84:87]
	v_mfma_f32_16x16x32_bf16 v[76:79], v[178:181], v[240:243], v[76:79]
	v_mfma_f32_16x16x32_bf16 v[68:71], v[208:211], v[240:243], v[68:71]
	s_setprio 3
	s_barrier
	s_add_i32 s40, s61, s42
	s_add_i32 m0, s40, 0xffffff80
	ds_read_b128 v[212:215], v153 offset:49152
	ds_read_b128 v[216:219], v153 offset:50176
	ds_read_b128 v[220:223], v153 offset:51200
	ds_read_b128 v[224:227], v153 offset:52224
	ds_read_b128 v[228:231], v153 offset:53248
	ds_read_b128 v[232:235], v153 offset:54272
	ds_read_b128 v[236:239], v153 offset:55296
	ds_read_b128 v[240:243], v153 offset:56320
	global_load_lds_dwordx4 v2, s[38:39] offset:128
	s_add_i32 m0, s40, 0x1f80
	s_add_i32 s40, s62, s42
	global_load_lds_dwordx4 v132, s[38:39] offset:128
	s_add_u32 s38, s38, 0x80080
	s_addc_u32 s39, s39, 0
	s_mov_b32 m0, s40
	s_nop 0
	global_load_lds_dwordx4 v2, s[38:39]
	s_add_i32 m0, s40, 0x2000
	s_nop 0
	global_load_lds_dwordx4 v132, s[38:39]
	s_mov_b32 m0, s51
	s_nop 0
	global_load_lds_dwordx4 v136, s[100:101]
	s_mov_b32 m0, s53
	s_nop 0
	global_load_lds_dwordx4 v134, s[100:101]
	s_waitcnt vmcnt(8) lgkmcnt(0)
	s_setprio 0
	s_barrier
	v_mfma_f32_16x16x32_bf16 v[64:67], v[142:145], v[212:215], v[64:67]
	v_mfma_f32_16x16x32_bf16 v[56:59], v[154:157], v[212:215], v[56:59]
	v_mfma_f32_16x16x32_bf16 v[48:51], v[142:145], v[220:223], v[48:51]
	v_mfma_f32_16x16x32_bf16 v[40:43], v[154:157], v[220:223], v[40:43]
	v_mfma_f32_16x16x32_bf16 v[32:35], v[142:145], v[228:231], v[32:35]
	v_mfma_f32_16x16x32_bf16 v[24:27], v[154:157], v[228:231], v[24:27]
	v_mfma_f32_16x16x32_bf16 v[16:19], v[142:145], v[236:239], v[16:19]
	v_mfma_f32_16x16x32_bf16 v[8:11], v[154:157], v[236:239], v[8:11]
	v_mfma_f32_16x16x32_bf16 v[64:67], v[146:149], v[216:219], v[64:67]
	v_mfma_f32_16x16x32_bf16 v[56:59], v[158:161], v[216:219], v[56:59]
	v_mfma_f32_16x16x32_bf16 v[48:51], v[146:149], v[224:227], v[48:51]
	v_mfma_f32_16x16x32_bf16 v[40:43], v[158:161], v[224:227], v[40:43]
	v_mfma_f32_16x16x32_bf16 v[32:35], v[146:149], v[232:235], v[32:35]
	v_mfma_f32_16x16x32_bf16 v[24:27], v[158:161], v[232:235], v[24:27]
	v_mfma_f32_16x16x32_bf16 v[16:19], v[146:149], v[240:243], v[16:19]
	v_mfma_f32_16x16x32_bf16 v[8:11], v[158:161], v[240:243], v[8:11]
	v_mfma_f32_16x16x32_bf16 v[60:63], v[174:177], v[212:215], v[60:63]
	ds_read_b128 v[142:145], v249
	v_mfma_f32_16x16x32_bf16 v[52:55], v[204:207], v[212:215], v[52:55]
	ds_read_b128 v[146:149], v249 offset:1024
	v_mfma_f32_16x16x32_bf16 v[44:47], v[174:177], v[220:223], v[44:47]
	ds_read_b128 v[154:157], v249 offset:2048
	v_mfma_f32_16x16x32_bf16 v[36:39], v[204:207], v[220:223], v[36:39]
	ds_read_b128 v[158:161], v249 offset:3072
	v_mfma_f32_16x16x32_bf16 v[28:31], v[174:177], v[228:231], v[28:31]
	v_mfma_f32_16x16x32_bf16 v[20:23], v[204:207], v[228:231], v[20:23]
	v_mfma_f32_16x16x32_bf16 v[12:15], v[174:177], v[236:239], v[12:15]
	v_mfma_f32_16x16x32_bf16 v[4:7], v[204:207], v[236:239], v[4:7]
	v_mfma_f32_16x16x32_bf16 v[60:63], v[178:181], v[216:219], v[60:63]
	v_mfma_f32_16x16x32_bf16 v[52:55], v[208:211], v[216:219], v[52:55]
	v_mfma_f32_16x16x32_bf16 v[44:47], v[178:181], v[224:227], v[44:47]
	v_mfma_f32_16x16x32_bf16 v[36:39], v[208:211], v[224:227], v[36:39]
	v_mfma_f32_16x16x32_bf16 v[28:31], v[178:181], v[232:235], v[28:31]
	v_mfma_f32_16x16x32_bf16 v[20:23], v[208:211], v[232:235], v[20:23]
	v_mfma_f32_16x16x32_bf16 v[12:15], v[178:181], v[240:243], v[12:15]
	v_mfma_f32_16x16x32_bf16 v[4:7], v[208:211], v[240:243], v[4:7]
	s_setprio 3
	s_barrier
	s_add_i32 s60, s60, 2
	s_add_u32 s36, s36, 0x100
	s_addc_u32 s37, s37, 0
	s_add_u32 s58, s58, 0x100
	s_addc_u32 s59, s59, 0
	s_cmp_gt_u32 s60, 29
	s_cbranch_scc0 .LBB0_301
	s_branch .Lpost_p1
	.p2align 6
	s_nop 0

; __device__ __forceinline__ unsigned cvt_pk_bf16(float lo, float hi) { unsigned r; asm volatile("v_cvt_pk_bf16_f32 %0, %1, %2" : "=v"(r) : "v"(lo), "v"(hi)); return r; }
;     __device__ __forceinline__ void operator()(const f32x4 (&acc)[2][2][4][2], const Unit& u, int wr, int wc, int fr, int fq) const {
;     ...
;             for (int m = 0; m < 4; ++m) { bf16_t* rowp = O + (size_t)(row0 + ai * HALF + m * 16) * ldc + col0;
;                 const f32x2 r2 = (f32x2){rs[ai][m], rs[ai][m]}; f32x2 h2[4];
; #pragma unroll
;                 for (int n = 0; n < 2; ++n)
; #pragma unroll
;                     for (int q = 0; q < 2; ++q) { const f32x2 g = (f32x2){acc[ai][0][m][n][2 * q], acc[ai][0][m][n][2 * q + 1]} * r2, up = (f32x2){acc[ai][1][m][n][2 * q], acc[ai][1][m][n][2 * q + 1]} * r2;
;                         const f32x2 t = g * (-1.4426950408889634f); f32x2 d; d.x = __builtin_amdgcn_exp2f(t.x); d.y = __builtin_amdgcn_exp2f(t.y); d = d + 1.0f;
;                         f32x2 rc; rc.x = __builtin_amdgcn_rcpf(d.x); rc.y = __builtin_amdgcn_rcpf(d.y); h2[n * 2 + q] = (g * up) * rc; }
;                 u32x4 w; w.x = cvt_pk_bf16(h2[0].x, h2[0].y); w.y = cvt_pk_bf16(h2[1].x, h2[1].y); w.z = cvt_pk_bf16(h2[2].x, h2[2].y); w.w = cvt_pk_bf16(h2[3].x, h2[3].y);
;                 *(u32x4*)rowp = w; }
.Lpost_p1:
	s_and_b64 vcc, exec, s[8:9]
	s_cbranch_vccz .LBB0_304
	s_barrier
.LBB0_304:
	s_mov_b32 s32, 1
	ds_read2_b32 v[158:159], v151 offset1:16
	ds_read2_b32 v[148:149], v151 offset0:32 offset1:48
	ds_read2_b32 v[146:147], v151 offset0:128 offset1:144
	ds_read2_b32 v[142:143], v151 offset0:160 offset1:176
	v_lshl_or_b32 v156, s35, 7, v152
	s_waitcnt lgkmcnt(0)
	v_pk_mul_f32 v[128:129], v[128:129], v[158:159] op_sel_hi:[1,0]
	v_pk_mul_f32 v[124:125], v[124:125], v[158:159] op_sel_hi:[1,0]
	v_pk_mul_f32 v[162:163], v[128:129], s[18:19] op_sel_hi:[1,0]
	v_pk_mul_f32 v[124:125], v[128:129], v[124:125]
	v_pk_mul_f32 v[128:129], v[130:131], v[158:159] op_sel_hi:[1,0]
	v_pk_mul_f32 v[126:127], v[126:127], v[158:159] op_sel_hi:[1,0]
	v_pk_mul_f32 v[120:121], v[120:121], v[158:159] op_sel_hi:[1,0]
	v_pk_mul_f32 v[130:131], v[128:129], s[18:19] op_sel_hi:[1,0]
	v_pk_mul_f32 v[126:127], v[128:129], v[126:127]
	v_pk_mul_f32 v[128:129], v[120:121], s[18:19] op_sel_hi:[1,0]
	v_pk_mul_f32 v[116:117], v[116:117], v[158:159] op_sel_hi:[1,0]
	v_exp_f32_e32 v128, v128
	v_exp_f32_e32 v129, v129
	v_pk_mul_f32 v[116:117], v[120:121], v[116:117]
	v_exp_f32_e32 v162, v162
	v_exp_f32_e32 v163, v163
	v_pk_add_f32 v[128:129], v[128:129], 1.0 op_sel_hi:[1,0]
	v_exp_f32_e32 v130, v130
	v_rcp_f32_e32 v128, v128
	v_rcp_f32_e32 v129, v129
	v_exp_f32_e32 v131, v131
	v_pk_add_f32 v[162:163], v[162:163], 1.0 op_sel_hi:[1,0]
	v_pk_mul_f32 v[118:119], v[118:119], v[158:159] op_sel_hi:[1,0]
	v_pk_mul_f32 v[120:121], v[116:117], v[128:129]
	v_pk_mul_f32 v[116:117], v[122:123], v[158:159] op_sel_hi:[1,0]
	v_pk_add_f32 v[130:131], v[130:131], 1.0 op_sel_hi:[1,0]
	v_pk_mul_f32 v[122:123], v[116:117], s[18:19] op_sel_hi:[1,0]
	v_rcp_f32_e32 v162, v162
	v_exp_f32_e32 v122, v122
	v_exp_f32_e32 v123, v123
	v_rcp_f32_e32 v163, v163
	v_rcp_f32_e32 v130, v130
	v_rcp_f32_e32 v131, v131
	v_pk_add_f32 v[122:123], v[122:123], 1.0 op_sel_hi:[1,0]
	v_lshl_add_u32 v154, s34, 8, v1
	v_rcp_f32_e32 v122, v122
	v_rcp_f32_e32 v123, v123
	v_ashrrev_i32_e32 v157, 31, v156
	v_mov_b64_e32 v[144:145], s[6:7]
	s_movk_i32 s11, 0x2b00
	v_pk_mul_f32 v[116:117], v[116:117], v[118:119]
	v_mad_i64_i32 v[160:161], s[34:35], v154, s11, v[144:145]
	v_pk_mul_f32 v[122:123], v[116:117], v[122:123]
	v_lshlrev_b64 v[116:117], 1, v[156:157]
	v_pk_mul_f32 v[124:125], v[124:125], v[162:163]
	v_pk_mul_f32 v[126:127], v[126:127], v[130:131]
	v_lshl_add_u64 v[128:129], v[160:161], 0, v[116:117]
	v_cvt_pk_bf16_f32 v118, v124, v125
	v_cvt_pk_bf16_f32 v119, v126, v127
	v_cvt_pk_bf16_f32 v120, v120, v121
	v_cvt_pk_bf16_f32 v121, v122, v123
	global_store_dwordx4 v[128:129], v[118:121], off
	v_pk_mul_f32 v[96:97], v[96:97], v[148:149] op_sel_hi:[1,0]
	v_pk_mul_f32 v[92:93], v[92:93], v[148:149] op_sel_hi:[1,0]
	v_mov_b32_e32 v120, v159
	v_pk_mul_f32 v[112:113], v[112:113], v[120:121] op_sel_hi:[1,0]
	v_pk_mul_f32 v[108:109], v[108:109], v[120:121] op_sel_hi:[1,0]
	v_pk_mul_f32 v[122:123], v[112:113], s[18:19] op_sel_hi:[1,0]
	v_pk_mul_f32 v[108:109], v[112:113], v[108:109]
	v_pk_mul_f32 v[112:113], v[114:115], v[120:121] op_sel_hi:[1,0]
	v_pk_mul_f32 v[110:111], v[110:111], v[120:121] op_sel_hi:[1,0]
	v_pk_mul_f32 v[104:105], v[104:105], v[120:121] op_sel_hi:[1,0]
	v_pk_mul_f32 v[114:115], v[112:113], s[18:19] op_sel_hi:[1,0]
	v_pk_mul_f32 v[110:111], v[112:113], v[110:111]
	v_pk_mul_f32 v[112:113], v[104:105], s[18:19] op_sel_hi:[1,0]
	v_pk_mul_f32 v[100:101], v[100:101], v[120:121] op_sel_hi:[1,0]
	v_exp_f32_e32 v112, v112
	v_exp_f32_e32 v113, v113
	v_pk_mul_f32 v[100:101], v[104:105], v[100:101]
	v_exp_f32_e32 v122, v122
	v_exp_f32_e32 v123, v123
	v_pk_add_f32 v[112:113], v[112:113], 1.0 op_sel_hi:[1,0]
	v_exp_f32_e32 v114, v114
	v_rcp_f32_e32 v112, v112
	v_rcp_f32_e32 v113, v113
	v_exp_f32_e32 v115, v115
	v_pk_add_f32 v[122:123], v[122:123], 1.0 op_sel_hi:[1,0]
	v_or_b32_e32 v118, 16, v154
	v_pk_mul_f32 v[104:105], v[100:101], v[112:113]
	v_pk_mul_f32 v[100:101], v[106:107], v[120:121] op_sel_hi:[1,0]
	v_pk_add_f32 v[114:115], v[114:115], 1.0 op_sel_hi:[1,0]
	v_pk_mul_f32 v[106:107], v[100:101], s[18:19] op_sel_hi:[1,0]
	v_rcp_f32_e32 v122, v122
	v_exp_f32_e32 v106, v106
	v_exp_f32_e32 v107, v107
	v_rcp_f32_e32 v123, v123
	v_rcp_f32_e32 v114, v114
	v_rcp_f32_e32 v115, v115
	v_pk_add_f32 v[106:107], v[106:107], 1.0 op_sel_hi:[1,0]
	v_pk_mul_f32 v[102:103], v[102:103], v[120:121] op_sel_hi:[1,0]
	v_rcp_f32_e32 v106, v106
	v_rcp_f32_e32 v107, v107
	v_mad_i64_i32 v[118:119], s[34:35], v118, s11, v[144:145]
	v_pk_mul_f32 v[100:101], v[100:101], v[102:103]
	v_pk_mul_f32 v[108:109], v[108:109], v[122:123]
	v_pk_mul_f32 v[110:111], v[110:111], v[114:115]
	v_pk_mul_f32 v[106:107], v[100:101], v[106:107]
	v_lshl_add_u64 v[112:113], v[118:119], 0, v[116:117]
	v_cvt_pk_bf16_f32 v100, v108, v109
	v_cvt_pk_bf16_f32 v101, v110, v111
	v_cvt_pk_bf16_f32 v102, v104, v105
	v_cvt_pk_bf16_f32 v103, v106, v107
	global_store_dwordx4 v[112:113], v[100:103], off
	v_pk_mul_f32 v[92:93], v[96:97], v[92:93]
	v_pk_mul_f32 v[94:95], v[94:95], v[148:149] op_sel_hi:[1,0]
	v_pk_mul_f32 v[102:103], v[96:97], s[18:19] op_sel_hi:[1,0]
	v_pk_mul_f32 v[96:97], v[98:99], v[148:149] op_sel_hi:[1,0]
	v_pk_mul_f32 v[88:89], v[88:89], v[148:149] op_sel_hi:[1,0]
	v_pk_mul_f32 v[98:99], v[96:97], s[18:19] op_sel_hi:[1,0]
	v_pk_mul_f32 v[94:95], v[96:97], v[94:95]
	v_pk_mul_f32 v[96:97], v[88:89], s[18:19] op_sel_hi:[1,0]
	v_pk_mul_f32 v[84:85], v[84:85], v[148:149] op_sel_hi:[1,0]
	v_exp_f32_e32 v96, v96
	v_exp_f32_e32 v97, v97
	v_pk_mul_f32 v[84:85], v[88:89], v[84:85]
	v_exp_f32_e32 v102, v102
	v_exp_f32_e32 v103, v103
	v_pk_add_f32 v[96:97], v[96:97], 1.0 op_sel_hi:[1,0]
; __device__ __forceinline__ unsigned cvt_pk_bf16(float lo, float hi) { unsigned r; asm volatile("v_cvt_pk_bf16_f32 %0, %1, %2" : "=v"(r) : "v"(lo), "v"(hi)); return r; }
;     __device__ __forceinline__ void operator()(const f32x4 (&acc)[2][2][4][2], const Unit& u, int wr, int wc, int fr, int fq) const {
;     ...
;             for (int m = 0; m < 4; ++m) { bf16_t* rowp = O + (size_t)(row0 + ai * HALF + m * 16) * ldc + col0;
;                 const f32x2 r2 = (f32x2){rs[ai][m], rs[ai][m]}; f32x2 h2[4];
; #pragma unroll
;                 for (int n = 0; n < 2; ++n)
; #pragma unroll
;                     for (int q = 0; q < 2; ++q) { const f32x2 g = (f32x2){acc[ai][0][m][n][2 * q], acc[ai][0][m][n][2 * q + 1]} * r2, up = (f32x2){acc[ai][1][m][n][2 * q], acc[ai][1][m][n][2 * q + 1]} * r2;
;                         const f32x2 t = g * (-1.4426950408889634f); f32x2 d; d.x = __builtin_amdgcn_exp2f(t.x); d.y = __builtin_amdgcn_exp2f(t.y); d = d + 1.0f;
;                         f32x2 rc; rc.x = __builtin_amdgcn_rcpf(d.x); rc.y = __builtin_amdgcn_rcpf(d.y); h2[n * 2 + q] = (g * up) * rc; }
;                 u32x4 w; w.x = cvt_pk_bf16(h2[0].x, h2[0].y); w.y = cvt_pk_bf16(h2[1].x, h2[1].y); w.z = cvt_pk_bf16(h2[2].x, h2[2].y); w.w = cvt_pk_bf16(h2[3].x, h2[3].y);
;                 *(u32x4*)rowp = w; }
	v_exp_f32_e32 v98, v98
	v_rcp_f32_e32 v96, v96
	v_rcp_f32_e32 v97, v97
	v_exp_f32_e32 v99, v99
	v_pk_add_f32 v[102:103], v[102:103], 1.0 op_sel_hi:[1,0]
	v_or_b32_e32 v100, 32, v154
	v_pk_mul_f32 v[88:89], v[84:85], v[96:97]
	v_pk_mul_f32 v[84:85], v[90:91], v[148:149] op_sel_hi:[1,0]
	v_pk_add_f32 v[98:99], v[98:99], 1.0 op_sel_hi:[1,0]
	v_pk_mul_f32 v[90:91], v[84:85], s[18:19] op_sel_hi:[1,0]
	v_rcp_f32_e32 v102, v102
	v_exp_f32_e32 v90, v90
	v_exp_f32_e32 v91, v91
	v_rcp_f32_e32 v103, v103
	v_rcp_f32_e32 v98, v98
	v_rcp_f32_e32 v99, v99
	v_pk_add_f32 v[90:91], v[90:91], 1.0 op_sel_hi:[1,0]
	v_pk_mul_f32 v[86:87], v[86:87], v[148:149] op_sel_hi:[1,0]
	v_rcp_f32_e32 v90, v90
	v_rcp_f32_e32 v91, v91
	v_mad_i64_i32 v[100:101], s[34:35], v100, s11, v[144:145]
	v_pk_mul_f32 v[84:85], v[84:85], v[86:87]
	v_pk_mul_f32 v[92:93], v[92:93], v[102:103]
	v_pk_mul_f32 v[94:95], v[94:95], v[98:99]
	v_pk_mul_f32 v[90:91], v[84:85], v[90:91]
	v_lshl_add_u64 v[96:97], v[100:101], 0, v[116:117]
	v_cvt_pk_bf16_f32 v84, v92, v93
	v_cvt_pk_bf16_f32 v85, v94, v95
	v_cvt_pk_bf16_f32 v86, v88, v89
	v_cvt_pk_bf16_f32 v87, v90, v91
	global_store_dwordx4 v[96:97], v[84:87], off
	v_pk_mul_f32 v[64:65], v[64:65], v[146:147] op_sel_hi:[1,0]
	v_pk_mul_f32 v[60:61], v[60:61], v[146:147] op_sel_hi:[1,0]
	v_mov_b32_e32 v86, v149
	v_pk_mul_f32 v[80:81], v[80:81], v[86:87] op_sel_hi:[1,0]
	v_pk_mul_f32 v[76:77], v[76:77], v[86:87] op_sel_hi:[1,0]
	v_pk_mul_f32 v[88:89], v[80:81], s[18:19] op_sel_hi:[1,0]
	v_pk_mul_f32 v[76:77], v[80:81], v[76:77]
	v_pk_mul_f32 v[80:81], v[82:83], v[86:87] op_sel_hi:[1,0]
	v_pk_mul_f32 v[78:79], v[78:79], v[86:87] op_sel_hi:[1,0]
	v_pk_mul_f32 v[72:73], v[72:73], v[86:87] op_sel_hi:[1,0]
	v_pk_mul_f32 v[82:83], v[80:81], s[18:19] op_sel_hi:[1,0]
	v_pk_mul_f32 v[78:79], v[80:81], v[78:79]
	v_pk_mul_f32 v[80:81], v[72:73], s[18:19] op_sel_hi:[1,0]
	v_pk_mul_f32 v[68:69], v[68:69], v[86:87] op_sel_hi:[1,0]
	v_exp_f32_e32 v80, v80
	v_exp_f32_e32 v81, v81
	v_pk_mul_f32 v[68:69], v[72:73], v[68:69]
	v_exp_f32_e32 v88, v88
	v_exp_f32_e32 v89, v89
	v_pk_add_f32 v[80:81], v[80:81], 1.0 op_sel_hi:[1,0]
	v_exp_f32_e32 v82, v82
	v_rcp_f32_e32 v80, v80
	v_rcp_f32_e32 v81, v81
	v_exp_f32_e32 v83, v83
	v_pk_add_f32 v[88:89], v[88:89], 1.0 op_sel_hi:[1,0]
	v_or_b32_e32 v84, 48, v154
	v_pk_mul_f32 v[72:73], v[68:69], v[80:81]
	v_pk_mul_f32 v[68:69], v[74:75], v[86:87] op_sel_hi:[1,0]
	v_pk_add_f32 v[82:83], v[82:83], 1.0 op_sel_hi:[1,0]
	v_pk_mul_f32 v[74:75], v[68:69], s[18:19] op_sel_hi:[1,0]
	v_rcp_f32_e32 v88, v88
	v_exp_f32_e32 v74, v74
	v_exp_f32_e32 v75, v75
	v_rcp_f32_e32 v89, v89
	v_rcp_f32_e32 v82, v82
	v_rcp_f32_e32 v83, v83
	v_pk_add_f32 v[74:75], v[74:75], 1.0 op_sel_hi:[1,0]
	v_pk_mul_f32 v[70:71], v[70:71], v[86:87] op_sel_hi:[1,0]
	v_rcp_f32_e32 v74, v74
	v_rcp_f32_e32 v75, v75
	v_mad_i64_i32 v[84:85], s[34:35], v84, s11, v[144:145]
	v_pk_mul_f32 v[68:69], v[68:69], v[70:71]
	v_pk_mul_f32 v[76:77], v[76:77], v[88:89]
	v_pk_mul_f32 v[78:79], v[78:79], v[82:83]
	v_pk_mul_f32 v[74:75], v[68:69], v[74:75]
	v_lshl_add_u64 v[80:81], v[84:85], 0, v[116:117]
	v_cvt_pk_bf16_f32 v68, v76, v77
	v_cvt_pk_bf16_f32 v69, v78, v79
	v_cvt_pk_bf16_f32 v70, v72, v73
	v_cvt_pk_bf16_f32 v71, v74, v75
	global_store_dwordx4 v[80:81], v[68:71], off
	v_pk_mul_f32 v[60:61], v[64:65], v[60:61]
	v_pk_mul_f32 v[62:63], v[62:63], v[146:147] op_sel_hi:[1,0]
	v_pk_mul_f32 v[70:71], v[64:65], s[18:19] op_sel_hi:[1,0]
	v_pk_mul_f32 v[64:65], v[66:67], v[146:147] op_sel_hi:[1,0]
	v_pk_mul_f32 v[56:57], v[56:57], v[146:147] op_sel_hi:[1,0]
	v_pk_mul_f32 v[66:67], v[64:65], s[18:19] op_sel_hi:[1,0]
	v_pk_mul_f32 v[62:63], v[64:65], v[62:63]
	v_pk_mul_f32 v[64:65], v[56:57], s[18:19] op_sel_hi:[1,0]
	v_pk_mul_f32 v[52:53], v[52:53], v[146:147] op_sel_hi:[1,0]
	v_exp_f32_e32 v64, v64
	v_exp_f32_e32 v65, v65
	v_pk_mul_f32 v[52:53], v[56:57], v[52:53]
	v_exp_f32_e32 v70, v70
	v_exp_f32_e32 v71, v71
	v_pk_add_f32 v[64:65], v[64:65], 1.0 op_sel_hi:[1,0]
	v_exp_f32_e32 v66, v66
	v_rcp_f32_e32 v64, v64
	v_rcp_f32_e32 v65, v65
	v_exp_f32_e32 v67, v67
	v_pk_add_f32 v[70:71], v[70:71], 1.0 op_sel_hi:[1,0]
	v_add_u32_e32 v68, 0x80, v154
	v_pk_mul_f32 v[56:57], v[52:53], v[64:65]
	v_pk_mul_f32 v[52:53], v[58:59], v[146:147] op_sel_hi:[1,0]
	v_pk_add_f32 v[66:67], v[66:67], 1.0 op_sel_hi:[1,0]
	v_pk_mul_f32 v[58:59], v[52:53], s[18:19] op_sel_hi:[1,0]
	v_rcp_f32_e32 v70, v70
	v_exp_f32_e32 v58, v58
	v_exp_f32_e32 v59, v59
	v_rcp_f32_e32 v71, v71
	v_rcp_f32_e32 v66, v66
	v_rcp_f32_e32 v67, v67
	v_pk_add_f32 v[58:59], v[58:59], 1.0 op_sel_hi:[1,0]
	v_pk_mul_f32 v[54:55], v[54:55], v[146:147] op_sel_hi:[1,0]
	v_rcp_f32_e32 v58, v58
	v_rcp_f32_e32 v59, v59
	v_mad_i64_i32 v[68:69], s[34:35], v68, s11, v[144:145]
	v_pk_mul_f32 v[52:53], v[52:53], v[54:55]
	v_pk_mul_f32 v[60:61], v[60:61], v[70:71]
	v_pk_mul_f32 v[62:63], v[62:63], v[66:67]
	v_pk_mul_f32 v[58:59], v[52:53], v[58:59]
	v_lshl_add_u64 v[64:65], v[68:69], 0, v[116:117]
	v_cvt_pk_bf16_f32 v52, v60, v61
	v_cvt_pk_bf16_f32 v53, v62, v63
	v_cvt_pk_bf16_f32 v54, v56, v57
	v_cvt_pk_bf16_f32 v55, v58, v59
	global_store_dwordx4 v[64:65], v[52:55], off
	v_pk_mul_f32 v[32:33], v[32:33], v[142:143] op_sel_hi:[1,0]
	v_pk_mul_f32 v[28:29], v[28:29], v[142:143] op_sel_hi:[1,0]
	v_mov_b32_e32 v54, v147
	v_pk_mul_f32 v[48:49], v[48:49], v[54:55] op_sel_hi:[1,0]
	v_pk_mul_f32 v[44:45], v[44:45], v[54:55] op_sel_hi:[1,0]
	v_pk_mul_f32 v[56:57], v[48:49], s[18:19] op_sel_hi:[1,0]
	v_pk_mul_f32 v[44:45], v[48:49], v[44:45]
	v_pk_mul_f32 v[48:49], v[50:51], v[54:55] op_sel_hi:[1,0]
	v_pk_mul_f32 v[46:47], v[46:47], v[54:55] op_sel_hi:[1,0]
; __device__ __forceinline__ unsigned cvt_pk_bf16(float lo, float hi) { unsigned r; asm volatile("v_cvt_pk_bf16_f32 %0, %1, %2" : "=v"(r) : "v"(lo), "v"(hi)); return r; }
;     __device__ __forceinline__ void operator()(const f32x4 (&acc)[2][2][4][2], const Unit& u, int wr, int wc, int fr, int fq) const {
;     ...
;             for (int m = 0; m < 4; ++m) { bf16_t* rowp = O + (size_t)(row0 + ai * HALF + m * 16) * ldc + col0;
;                 const f32x2 r2 = (f32x2){rs[ai][m], rs[ai][m]}; f32x2 h2[4];
; #pragma unroll
;                 for (int n = 0; n < 2; ++n)
; #pragma unroll
;                     for (int q = 0; q < 2; ++q) { const f32x2 g = (f32x2){acc[ai][0][m][n][2 * q], acc[ai][0][m][n][2 * q + 1]} * r2, up = (f32x2){acc[ai][1][m][n][2 * q], acc[ai][1][m][n][2 * q + 1]} * r2;
;                         const f32x2 t = g * (-1.4426950408889634f); f32x2 d; d.x = __builtin_amdgcn_exp2f(t.x); d.y = __builtin_amdgcn_exp2f(t.y); d = d + 1.0f;
;                         f32x2 rc; rc.x = __builtin_amdgcn_rcpf(d.x); rc.y = __builtin_amdgcn_rcpf(d.y); h2[n * 2 + q] = (g * up) * rc; }
;                 u32x4 w; w.x = cvt_pk_bf16(h2[0].x, h2[0].y); w.y = cvt_pk_bf16(h2[1].x, h2[1].y); w.z = cvt_pk_bf16(h2[2].x, h2[2].y); w.w = cvt_pk_bf16(h2[3].x, h2[3].y);
;                 *(u32x4*)rowp = w; }
	v_pk_mul_f32 v[40:41], v[40:41], v[54:55] op_sel_hi:[1,0]
	v_pk_mul_f32 v[50:51], v[48:49], s[18:19] op_sel_hi:[1,0]
	v_pk_mul_f32 v[46:47], v[48:49], v[46:47]
	v_pk_mul_f32 v[48:49], v[40:41], s[18:19] op_sel_hi:[1,0]
	v_pk_mul_f32 v[36:37], v[36:37], v[54:55] op_sel_hi:[1,0]
	v_exp_f32_e32 v48, v48
	v_exp_f32_e32 v49, v49
	v_pk_mul_f32 v[36:37], v[40:41], v[36:37]
	v_exp_f32_e32 v56, v56
	v_exp_f32_e32 v57, v57
	v_pk_add_f32 v[48:49], v[48:49], 1.0 op_sel_hi:[1,0]
	v_exp_f32_e32 v50, v50
	v_rcp_f32_e32 v48, v48
	v_rcp_f32_e32 v49, v49
	v_exp_f32_e32 v51, v51
	v_pk_add_f32 v[56:57], v[56:57], 1.0 op_sel_hi:[1,0]
	v_add_u32_e32 v52, 0x90, v154
	v_pk_mul_f32 v[40:41], v[36:37], v[48:49]
	v_pk_mul_f32 v[36:37], v[42:43], v[54:55] op_sel_hi:[1,0]
	v_pk_add_f32 v[50:51], v[50:51], 1.0 op_sel_hi:[1,0]
	v_pk_mul_f32 v[42:43], v[36:37], s[18:19] op_sel_hi:[1,0]
	v_rcp_f32_e32 v56, v56
	v_exp_f32_e32 v42, v42
	v_exp_f32_e32 v43, v43
	v_rcp_f32_e32 v57, v57
	v_rcp_f32_e32 v50, v50
	v_rcp_f32_e32 v51, v51
	v_pk_add_f32 v[42:43], v[42:43], 1.0 op_sel_hi:[1,0]
	v_pk_mul_f32 v[38:39], v[38:39], v[54:55] op_sel_hi:[1,0]
	v_rcp_f32_e32 v42, v42
	v_rcp_f32_e32 v43, v43
	v_mad_i64_i32 v[52:53], s[34:35], v52, s11, v[144:145]
	v_pk_mul_f32 v[36:37], v[36:37], v[38:39]
	v_pk_mul_f32 v[44:45], v[44:45], v[56:57]
	v_pk_mul_f32 v[46:47], v[46:47], v[50:51]
	v_pk_mul_f32 v[42:43], v[36:37], v[42:43]
	v_lshl_add_u64 v[48:49], v[52:53], 0, v[116:117]
	v_cvt_pk_bf16_f32 v36, v44, v45
	v_cvt_pk_bf16_f32 v37, v46, v47
	v_cvt_pk_bf16_f32 v38, v40, v41
	v_cvt_pk_bf16_f32 v39, v42, v43
	global_store_dwordx4 v[48:49], v[36:39], off
	v_pk_mul_f32 v[28:29], v[32:33], v[28:29]
	v_pk_mul_f32 v[30:31], v[30:31], v[142:143] op_sel_hi:[1,0]
	v_pk_mul_f32 v[38:39], v[32:33], s[18:19] op_sel_hi:[1,0]
	v_pk_mul_f32 v[32:33], v[34:35], v[142:143] op_sel_hi:[1,0]
	v_pk_mul_f32 v[24:25], v[24:25], v[142:143] op_sel_hi:[1,0]
	v_pk_mul_f32 v[34:35], v[32:33], s[18:19] op_sel_hi:[1,0]
	v_pk_mul_f32 v[30:31], v[32:33], v[30:31]
	v_pk_mul_f32 v[32:33], v[24:25], s[18:19] op_sel_hi:[1,0]
	v_pk_mul_f32 v[20:21], v[20:21], v[142:143] op_sel_hi:[1,0]
	v_exp_f32_e32 v32, v32
	v_exp_f32_e32 v33, v33
	v_pk_mul_f32 v[20:21], v[24:25], v[20:21]
	v_exp_f32_e32 v38, v38
	v_exp_f32_e32 v39, v39
	v_pk_add_f32 v[32:33], v[32:33], 1.0 op_sel_hi:[1,0]
	v_exp_f32_e32 v34, v34
	v_rcp_f32_e32 v32, v32
	v_rcp_f32_e32 v33, v33
	v_exp_f32_e32 v35, v35
	v_pk_add_f32 v[38:39], v[38:39], 1.0 op_sel_hi:[1,0]
	v_add_u32_e32 v36, 0xa0, v154
	v_pk_mul_f32 v[24:25], v[20:21], v[32:33]
	v_pk_mul_f32 v[20:21], v[26:27], v[142:143] op_sel_hi:[1,0]
	v_pk_add_f32 v[34:35], v[34:35], 1.0 op_sel_hi:[1,0]
	v_pk_mul_f32 v[26:27], v[20:21], s[18:19] op_sel_hi:[1,0]
	v_rcp_f32_e32 v38, v38
	v_exp_f32_e32 v26, v26
	v_exp_f32_e32 v27, v27
	v_rcp_f32_e32 v39, v39
	v_rcp_f32_e32 v34, v34
	v_rcp_f32_e32 v35, v35
	v_pk_add_f32 v[26:27], v[26:27], 1.0 op_sel_hi:[1,0]
	v_pk_mul_f32 v[22:23], v[22:23], v[142:143] op_sel_hi:[1,0]
	v_rcp_f32_e32 v26, v26
	v_rcp_f32_e32 v27, v27
	v_mad_i64_i32 v[36:37], s[34:35], v36, s11, v[144:145]
	v_pk_mul_f32 v[20:21], v[20:21], v[22:23]
	v_pk_mul_f32 v[28:29], v[28:29], v[38:39]
	v_pk_mul_f32 v[30:31], v[30:31], v[34:35]
	v_pk_mul_f32 v[26:27], v[20:21], v[26:27]
	v_lshl_add_u64 v[32:33], v[36:37], 0, v[116:117]
	v_cvt_pk_bf16_f32 v20, v28, v29
	v_cvt_pk_bf16_f32 v21, v30, v31
	v_cvt_pk_bf16_f32 v22, v24, v25
	v_cvt_pk_bf16_f32 v23, v26, v27
	global_store_dwordx4 v[32:33], v[20:23], off
	s_andn2_b64 vcc, exec, s[0:1]
	s_nop 0
	v_mov_b32_e32 v22, v143
	v_pk_mul_f32 v[16:17], v[16:17], v[22:23] op_sel_hi:[1,0]
	v_pk_mul_f32 v[12:13], v[12:13], v[22:23] op_sel_hi:[1,0]
	v_pk_mul_f32 v[24:25], v[16:17], s[18:19] op_sel_hi:[1,0]
	v_pk_mul_f32 v[12:13], v[16:17], v[12:13]
	v_pk_mul_f32 v[16:17], v[18:19], v[22:23] op_sel_hi:[1,0]
	v_pk_mul_f32 v[14:15], v[14:15], v[22:23] op_sel_hi:[1,0]
	v_pk_mul_f32 v[8:9], v[8:9], v[22:23] op_sel_hi:[1,0]
	v_pk_mul_f32 v[18:19], v[16:17], s[18:19] op_sel_hi:[1,0]
	v_pk_mul_f32 v[14:15], v[16:17], v[14:15]
	v_pk_mul_f32 v[16:17], v[8:9], s[18:19] op_sel_hi:[1,0]
	v_pk_mul_f32 v[4:5], v[4:5], v[22:23] op_sel_hi:[1,0]
	v_exp_f32_e32 v16, v16
	v_exp_f32_e32 v17, v17
	v_pk_mul_f32 v[4:5], v[8:9], v[4:5]
	v_exp_f32_e32 v24, v24
	v_exp_f32_e32 v25, v25
	v_pk_add_f32 v[16:17], v[16:17], 1.0 op_sel_hi:[1,0]
	v_exp_f32_e32 v18, v18
	v_rcp_f32_e32 v16, v16
	v_rcp_f32_e32 v17, v17
	v_exp_f32_e32 v19, v19
	v_pk_add_f32 v[24:25], v[24:25], 1.0 op_sel_hi:[1,0]
	v_add_u32_e32 v20, 0xb0, v154
	v_pk_mul_f32 v[8:9], v[4:5], v[16:17]
	v_pk_mul_f32 v[4:5], v[10:11], v[22:23] op_sel_hi:[1,0]
	v_pk_add_f32 v[18:19], v[18:19], 1.0 op_sel_hi:[1,0]
	v_pk_mul_f32 v[10:11], v[4:5], s[18:19] op_sel_hi:[1,0]
	v_rcp_f32_e32 v24, v24
	v_exp_f32_e32 v10, v10
	v_exp_f32_e32 v11, v11
	v_rcp_f32_e32 v25, v25
	v_rcp_f32_e32 v18, v18
	v_rcp_f32_e32 v19, v19
	v_pk_add_f32 v[10:11], v[10:11], 1.0 op_sel_hi:[1,0]
	v_mad_i64_i32 v[20:21], s[34:35], v20, s11, v[144:145]
	v_rcp_f32_e32 v10, v10
	v_rcp_f32_e32 v11, v11
	v_pk_mul_f32 v[6:7], v[6:7], v[22:23] op_sel_hi:[1,0]
	v_lshl_add_u64 v[16:17], v[20:21], 0, v[116:117]
	v_pk_mul_f32 v[4:5], v[4:5], v[6:7]
	s_mov_b64 s[34:35], -1
	v_pk_mul_f32 v[12:13], v[12:13], v[24:25]
	v_pk_mul_f32 v[14:15], v[14:15], v[18:19]
	v_pk_mul_f32 v[10:11], v[4:5], v[10:11]
	v_cvt_pk_bf16_f32 v4, v12, v13
	v_cvt_pk_bf16_f32 v5, v14, v15
	v_cvt_pk_bf16_f32 v6, v8, v9
	s_nop 0
	v_cvt_pk_bf16_f32 v7, v10, v11
	global_store_dwordx4 v[16:17], v[4:7], off
	s_cbranch_vccnz .LBB0_297
	s_andn2_b64 vcc, exec, s[4:5]
	s_cbranch_vccnz .LBB0_296
	s_barrier
	s_branch .LBB0_296
